# P0: nt (streaming) hint on the read-once f32 weight loads of convert_weights and mod_gemv, so they do not displace x / converted weights from cache
# speedup vs baseline: 1.0123x; 1.0123x over previous
.LBB0_12:
	v_add_co_u32_e32 v10, vcc, 0xfffa0000, v6
	global_load_dword v8, v[6:7], off nt
	s_nop 0
	v_addc_co_u32_e32 v11, vcc, -1, v7, vcc
	v_add_co_u32_e32 v34, vcc, 0xfffa6000, v6
	v_add_u32_e32 v32, s13, v28
	s_nop 0
	v_addc_co_u32_e32 v35, vcc, -1, v7, vcc
	v_add_co_u32_e32 v38, vcc, 0xfffac000, v6
	global_load_dword v10, v[10:11], off nt
	s_nop 0
	global_load_dword v34, v[34:35], off nt
	v_addc_co_u32_e32 v39, vcc, -1, v7, vcc
	v_add_co_u32_e32 v40, vcc, 0xfffb2000, v6
	ds_bpermute_b32 v13, v32, v30
	s_nop 0
	v_addc_co_u32_e32 v41, vcc, -1, v7, vcc
	v_add_co_u32_e32 v42, vcc, 0xfffb8000, v6
	global_load_dword v38, v[38:39], off nt
	s_nop 0
	global_load_dword v40, v[40:41], off nt
	v_addc_co_u32_e32 v43, vcc, -1, v7, vcc
	v_add_co_u32_e32 v44, vcc, 0xfffbe000, v6
	ds_bpermute_b32 v12, v32, v31
	s_nop 0
	v_addc_co_u32_e32 v45, vcc, -1, v7, vcc
	v_add_co_u32_e32 v46, vcc, 0xfffc4000, v6
	global_load_dword v42, v[42:43], off nt
	s_nop 0
	global_load_dword v44, v[44:45], off nt
	v_addc_co_u32_e32 v47, vcc, -1, v7, vcc
	v_add_co_u32_e32 v48, vcc, 0xfffca000, v6
	ds_bpermute_b32 v15, v32, v30 offset:4
	s_nop 0
	v_addc_co_u32_e32 v49, vcc, -1, v7, vcc
	v_add_co_u32_e32 v50, vcc, 0xfffd0000, v6
	global_load_dword v46, v[46:47], off nt
	s_nop 0
	global_load_dword v48, v[48:49], off nt
	v_addc_co_u32_e32 v51, vcc, -1, v7, vcc
	v_add_co_u32_e32 v52, vcc, 0xfffd6000, v6
	ds_bpermute_b32 v14, v32, v31 offset:4
	s_nop 0
	v_addc_co_u32_e32 v53, vcc, -1, v7, vcc
	v_add_co_u32_e32 v54, vcc, 0xfffdc000, v6
	global_load_dword v50, v[50:51], off nt
	s_nop 0
	global_load_dword v52, v[52:53], off nt
	v_addc_co_u32_e32 v55, vcc, -1, v7, vcc
	v_add_co_u32_e32 v56, vcc, 0xfffe2000, v6
	ds_bpermute_b32 v17, v32, v30 offset:8
	s_nop 0
	v_addc_co_u32_e32 v57, vcc, -1, v7, vcc
	v_add_co_u32_e32 v58, vcc, 0xfffe8000, v6
	global_load_dword v54, v[54:55], off nt
	s_nop 0
	global_load_dword v56, v[56:57], off nt
	v_addc_co_u32_e32 v59, vcc, -1, v7, vcc
	v_add_co_u32_e32 v60, vcc, 0xfffee000, v6
	ds_bpermute_b32 v16, v32, v31 offset:8
	s_nop 0
	v_addc_co_u32_e32 v61, vcc, -1, v7, vcc
	v_add_co_u32_e32 v62, vcc, 0xffff4000, v6
	global_load_dword v58, v[58:59], off nt
	s_nop 0
	global_load_dword v60, v[60:61], off nt
	v_addc_co_u32_e32 v63, vcc, -1, v7, vcc
	v_add_co_u32_e32 v64, vcc, 0xffffa000, v6
	ds_bpermute_b32 v19, v32, v30 offset:12
	s_nop 0
	v_addc_co_u32_e32 v65, vcc, -1, v7, vcc
	v_add_co_u32_e32 v66, vcc, s12, v6
	global_load_dword v62, v[62:63], off nt
	s_nop 0
	global_load_dword v64, v[64:65], off nt
	v_addc_co_u32_e32 v67, vcc, 0, v7, vcc
	v_add_co_u32_e32 v68, vcc, s16, v6
	ds_bpermute_b32 v18, v32, v31 offset:12
	s_nop 0
	v_addc_co_u32_e32 v69, vcc, 0, v7, vcc
	v_add_co_u32_e32 v70, vcc, s17, v6
	global_load_dword v66, v[66:67], off nt
	s_nop 0
	global_load_dword v68, v[68:69], off nt
	v_addc_co_u32_e32 v71, vcc, 0, v7, vcc
	v_add_co_u32_e32 v72, vcc, s18, v6
	ds_bpermute_b32 v21, v32, v30 offset:16
	s_nop 0
	v_addc_co_u32_e32 v73, vcc, 0, v7, vcc
	v_add_co_u32_e32 v74, vcc, s19, v6
	global_load_dword v70, v[70:71], off nt
	s_nop 0
	global_load_dword v72, v[72:73], off nt
	v_addc_co_u32_e32 v75, vcc, 0, v7, vcc
	v_add_co_u32_e32 v76, vcc, s20, v6
	ds_bpermute_b32 v20, v32, v31 offset:16
	s_nop 0
	v_addc_co_u32_e32 v77, vcc, 0, v7, vcc
	v_add_co_u32_e32 v78, vcc, s21, v6
	global_load_dword v74, v[74:75], off nt
	s_nop 0
	global_load_dword v76, v[76:77], off nt
	v_addc_co_u32_e32 v79, vcc, 0, v7, vcc
	v_add_co_u32_e32 v80, vcc, s22, v6
	ds_bpermute_b32 v23, v32, v30 offset:20
	s_nop 0
	v_addc_co_u32_e32 v81, vcc, 0, v7, vcc
	v_add_co_u32_e32 v82, vcc, s23, v6
	global_load_dword v78, v[78:79], off nt
	s_nop 0
	global_load_dword v80, v[80:81], off nt
	v_addc_co_u32_e32 v83, vcc, 0, v7, vcc
	v_add_co_u32_e32 v84, vcc, s24, v6
	global_load_dword v82, v[82:83], off nt
	s_nop 0
	v_addc_co_u32_e32 v85, vcc, 0, v7, vcc
	v_add_co_u32_e32 v86, vcc, s25, v6
	ds_bpermute_b32 v22, v32, v31 offset:20
	s_nop 0
	v_addc_co_u32_e32 v87, vcc, 0, v7, vcc
	v_add_co_u32_e32 v88, vcc, s26, v6
	global_load_dword v84, v[84:85], off nt
	s_nop 0
	global_load_dword v86, v[86:87], off nt
	v_addc_co_u32_e32 v89, vcc, 0, v7, vcc
	v_add_co_u32_e32 v90, vcc, s27, v6
	s_waitcnt vmcnt(26) lgkmcnt(10)
	v_pk_fma_f32 v[2:3], v[12:13], v[10:11], v[2:3] op_sel_hi:[1,0,1]
	v_addc_co_u32_e32 v91, vcc, 0, v7, vcc
	v_add_co_u32_e32 v92, vcc, s28, v6
	global_load_dword v88, v[88:89], off nt
	s_nop 0
	global_load_dword v90, v[90:91], off nt
	v_addc_co_u32_e32 v93, vcc, 0, v7, vcc
	v_add_co_u32_e32 v94, vcc, 0x5a000, v6
	ds_bpermute_b32 v25, v32, v30 offset:24
	s_nop 0
	v_addc_co_u32_e32 v95, vcc, 0, v7, vcc
	global_load_dword v92, v[92:93], off nt
	s_nop 0
	global_load_dword v94, v[94:95], off nt
	ds_bpermute_b32 v24, v32, v31 offset:24
	s_waitcnt vmcnt(29) lgkmcnt(10)
	v_pk_fma_f32 v[2:3], v[14:15], v[34:35], v[2:3] op_sel_hi:[1,0,1]
	ds_bpermute_b32 v27, v32, v30 offset:28
	ds_bpermute_b32 v26, v32, v31 offset:28
	s_waitcnt vmcnt(28) lgkmcnt(10)
	v_pk_fma_f32 v[2:3], v[16:17], v[38:39], v[2:3] op_sel_hi:[1,0,1]
	ds_bpermute_b32 v37, v32, v30 offset:32
	ds_bpermute_b32 v36, v32, v31 offset:32
	s_waitcnt vmcnt(27) lgkmcnt(10)
	v_pk_fma_f32 v[2:3], v[18:19], v[40:41], v[2:3] op_sel_hi:[1,0,1]
	ds_bpermute_b32 v97, v32, v30 offset:36
	ds_bpermute_b32 v96, v32, v31 offset:36
	s_waitcnt vmcnt(26) lgkmcnt(10)
	v_pk_fma_f32 v[2:3], v[20:21], v[42:43], v[2:3] op_sel_hi:[1,0,1]
	ds_bpermute_b32 v99, v32, v30 offset:40
	ds_bpermute_b32 v98, v32, v31 offset:40
	s_waitcnt vmcnt(25) lgkmcnt(10)
	v_pk_fma_f32 v[2:3], v[22:23], v[44:45], v[2:3] op_sel_hi:[1,0,1]
	ds_bpermute_b32 v101, v32, v30 offset:44
	ds_bpermute_b32 v100, v32, v31 offset:44
	s_waitcnt vmcnt(24) lgkmcnt(10)
	v_pk_fma_f32 v[2:3], v[24:25], v[46:47], v[2:3] op_sel_hi:[1,0,1]
	ds_bpermute_b32 v103, v32, v30 offset:48
	ds_bpermute_b32 v102, v32, v31 offset:48
	s_waitcnt vmcnt(23) lgkmcnt(10)
	v_pk_fma_f32 v[2:3], v[26:27], v[48:49], v[2:3] op_sel_hi:[1,0,1]
	ds_bpermute_b32 v105, v32, v30 offset:52
	ds_bpermute_b32 v104, v32, v31 offset:52
	s_waitcnt vmcnt(22) lgkmcnt(10)
	v_pk_fma_f32 v[2:3], v[36:37], v[50:51], v[2:3] op_sel_hi:[1,0,1]
	ds_bpermute_b32 v107, v32, v30 offset:56
	ds_bpermute_b32 v106, v32, v31 offset:56
	s_waitcnt vmcnt(21) lgkmcnt(10)
	v_pk_fma_f32 v[2:3], v[96:97], v[52:53], v[2:3] op_sel_hi:[1,0,1]
	ds_bpermute_b32 v109, v32, v30 offset:60
	ds_bpermute_b32 v108, v32, v31 offset:60
	s_waitcnt vmcnt(20) lgkmcnt(10)
	v_pk_fma_f32 v[2:3], v[98:99], v[54:55], v[2:3] op_sel_hi:[1,0,1]
	ds_bpermute_b32 v111, v32, v30 offset:64
	ds_bpermute_b32 v110, v32, v31 offset:64
	s_waitcnt vmcnt(19) lgkmcnt(10)
	v_pk_fma_f32 v[2:3], v[100:101], v[56:57], v[2:3] op_sel_hi:[1,0,1]
	ds_bpermute_b32 v113, v32, v30 offset:68
	ds_bpermute_b32 v112, v32, v31 offset:68
	s_waitcnt vmcnt(18) lgkmcnt(10)
	v_pk_fma_f32 v[2:3], v[102:103], v[58:59], v[2:3] op_sel_hi:[1,0,1]
	ds_bpermute_b32 v115, v32, v30 offset:72
	ds_bpermute_b32 v114, v32, v31 offset:72
	s_waitcnt vmcnt(17) lgkmcnt(10)
	v_pk_fma_f32 v[2:3], v[104:105], v[60:61], v[2:3] op_sel_hi:[1,0,1]
	ds_bpermute_b32 v117, v32, v30 offset:76
	ds_bpermute_b32 v116, v32, v31 offset:76
	s_waitcnt vmcnt(16) lgkmcnt(10)
	v_pk_fma_f32 v[2:3], v[106:107], v[62:63], v[2:3] op_sel_hi:[1,0,1]
	ds_bpermute_b32 v119, v32, v30 offset:80
	ds_bpermute_b32 v118, v32, v31 offset:80
	s_waitcnt vmcnt(15) lgkmcnt(10)
	v_pk_fma_f32 v[2:3], v[108:109], v[64:65], v[2:3] op_sel_hi:[1,0,1]
	ds_bpermute_b32 v121, v32, v30 offset:84
	ds_bpermute_b32 v120, v32, v31 offset:84
	s_waitcnt lgkmcnt(10)
	v_pk_fma_f32 v[2:3], v[110:111], v[8:9], v[2:3] op_sel_hi:[1,0,1]
	ds_bpermute_b32 v123, v32, v30 offset:88
	ds_bpermute_b32 v122, v32, v31 offset:88
	s_waitcnt vmcnt(14) lgkmcnt(10)
	v_pk_fma_f32 v[2:3], v[112:113], v[66:67], v[2:3] op_sel_hi:[1,0,1]
	ds_bpermute_b32 v125, v32, v30 offset:92
	ds_bpermute_b32 v124, v32, v31 offset:92
	s_waitcnt vmcnt(13) lgkmcnt(10)
	v_pk_fma_f32 v[2:3], v[114:115], v[68:69], v[2:3] op_sel_hi:[1,0,1]
	ds_bpermute_b32 v127, v32, v30 offset:96
	ds_bpermute_b32 v126, v32, v31 offset:96
	s_waitcnt vmcnt(12) lgkmcnt(10)
	v_pk_fma_f32 v[2:3], v[116:117], v[70:71], v[2:3] op_sel_hi:[1,0,1]
	ds_bpermute_b32 v129, v32, v30 offset:100
	ds_bpermute_b32 v128, v32, v31 offset:100
	s_waitcnt vmcnt(11) lgkmcnt(10)
	v_pk_fma_f32 v[2:3], v[118:119], v[72:73], v[2:3] op_sel_hi:[1,0,1]
	ds_bpermute_b32 v131, v32, v30 offset:104
	ds_bpermute_b32 v130, v32, v31 offset:104
	s_waitcnt vmcnt(10) lgkmcnt(10)
	v_pk_fma_f32 v[2:3], v[120:121], v[74:75], v[2:3] op_sel_hi:[1,0,1]
	ds_bpermute_b32 v133, v32, v30 offset:108
	ds_bpermute_b32 v132, v32, v31 offset:108
	s_waitcnt vmcnt(9) lgkmcnt(10)
	v_pk_fma_f32 v[2:3], v[122:123], v[76:77], v[2:3] op_sel_hi:[1,0,1]
	ds_bpermute_b32 v135, v32, v30 offset:112
	ds_bpermute_b32 v134, v32, v31 offset:112
	s_waitcnt vmcnt(8) lgkmcnt(10)
	v_pk_fma_f32 v[2:3], v[124:125], v[78:79], v[2:3] op_sel_hi:[1,0,1]
	ds_bpermute_b32 v137, v32, v30 offset:116
	ds_bpermute_b32 v136, v32, v31 offset:116
	s_waitcnt vmcnt(7) lgkmcnt(10)
	v_pk_fma_f32 v[2:3], v[126:127], v[80:81], v[2:3] op_sel_hi:[1,0,1]
	ds_bpermute_b32 v139, v32, v30 offset:120
	ds_bpermute_b32 v138, v32, v31 offset:120
	s_waitcnt vmcnt(6) lgkmcnt(10)
	v_pk_fma_f32 v[2:3], v[128:129], v[82:83], v[2:3] op_sel_hi:[1,0,1]
	ds_bpermute_b32 v33, v32, v30 offset:124
	ds_bpermute_b32 v32, v32, v31 offset:124
	s_waitcnt vmcnt(5) lgkmcnt(10)
	v_pk_fma_f32 v[2:3], v[130:131], v[84:85], v[2:3] op_sel_hi:[1,0,1]
	s_addk_i32 s13, 0x80
	s_waitcnt vmcnt(4) lgkmcnt(8)
	v_pk_fma_f32 v[2:3], v[132:133], v[86:87], v[2:3] op_sel_hi:[1,0,1]
	s_cmpk_eq_i32 s13, 0x100
	s_waitcnt vmcnt(3) lgkmcnt(6)
	v_pk_fma_f32 v[2:3], v[134:135], v[88:89], v[2:3] op_sel_hi:[1,0,1]
	v_lshl_add_u64 v[6:7], v[6:7], 0, s[8:9]
	s_waitcnt vmcnt(2) lgkmcnt(4)
	v_pk_fma_f32 v[2:3], v[136:137], v[90:91], v[2:3] op_sel_hi:[1,0,1]
	s_waitcnt vmcnt(1) lgkmcnt(2)
	v_pk_fma_f32 v[2:3], v[138:139], v[92:93], v[2:3] op_sel_hi:[1,0,1]
	s_waitcnt vmcnt(0) lgkmcnt(0)
	v_pk_fma_f32 v[2:3], v[32:33], v[94:95], v[2:3] op_sel_hi:[1,0,1]
	s_cbranch_scc0 .LBB0_12
	v_mul_f32_e32 v6, 0xbfb8aa3b, v29
	v_exp_f32_e32 v6, v6
	v_mul_f32_e32 v7, 0xbfb8aa3b, v9
	v_exp_f32_e32 v7, v7
	s_mov_b32 s8, 0
	v_add_f32_e32 v6, 1.0, v6
	v_div_scale_f32 v8, s[4:5], v6, v6, v29
	v_rcp_f32_e32 v10, v8
	v_div_scale_f32 v11, vcc, v29, v6, v29
	v_add_f32_e32 v7, 1.0, v7
	v_fma_f32 v12, -v8, v10, 1.0
	v_fmac_f32_e32 v10, v12, v10
	v_mul_f32_e32 v12, v11, v10
	v_fma_f32 v13, -v8, v12, v11
	v_fmac_f32_e32 v12, v13, v10
	v_fma_f32 v8, -v8, v12, v11
	v_div_scale_f32 v11, s[4:5], v7, v7, v9
	v_rcp_f32_e32 v13, v11
	v_div_fmas_f32 v8, v8, v10, v12
	v_div_fixup_f32 v24, v8, v6, v29
	s_mov_b64 s[4:5], 0x23a000
	v_fma_f32 v6, -v11, v13, 1.0
	v_fmac_f32_e32 v13, v6, v13
	v_div_scale_f32 v6, vcc, v9, v7, v9
	v_mul_f32_e32 v8, v6, v13
	v_fma_f32 v10, -v11, v8, v6
	v_fmac_f32_e32 v8, v10, v13
	v_fma_f32 v6, -v11, v8, v6
	v_div_fmas_f32 v6, v6, v13, v8
	v_div_fixup_f32 v25, v6, v7, v9
	v_lshl_add_u64 v[4:5], v[4:5], 0, s[4:5]
	s_mov_b64 s[4:5], 0xc0000
.LBB0_14:
	v_add_co_u32_e32 v6, vcc, 0xfff46000, v4
	v_add_u32_e32 v26, s8, v28
	s_nop 0
	v_addc_co_u32_e32 v7, vcc, -1, v5, vcc
	v_add_co_u32_e32 v30, vcc, 0xfff4c000, v4
	ds_bpermute_b32 v9, v26, v24
	s_nop 0
	v_addc_co_u32_e32 v31, vcc, -1, v5, vcc
	v_add_co_u32_e32 v34, vcc, 0xfff52000, v4
	global_load_dword v36, v[6:7], off nt
	global_load_dword v38, v[30:31], off nt
	v_addc_co_u32_e32 v35, vcc, -1, v5, vcc
	v_add_co_u32_e32 v6, vcc, 0xfff58000, v4
	ds_bpermute_b32 v8, v26, v25
	s_nop 0
	v_addc_co_u32_e32 v7, vcc, -1, v5, vcc
	v_add_co_u32_e32 v30, vcc, 0xfff5e000, v4
	global_load_dword v40, v[34:35], off nt
	global_load_dword v42, v[6:7], off nt
	v_addc_co_u32_e32 v31, vcc, -1, v5, vcc
	v_add_co_u32_e32 v6, vcc, 0xfff64000, v4
	ds_bpermute_b32 v11, v26, v24 offset:4
	s_nop 0
	v_addc_co_u32_e32 v7, vcc, -1, v5, vcc
	v_add_co_u32_e32 v34, vcc, 0xfff6a000, v4
	global_load_dword v44, v[30:31], off nt
	global_load_dword v46, v[6:7], off nt
	v_addc_co_u32_e32 v35, vcc, -1, v5, vcc
	v_add_co_u32_e32 v6, vcc, 0xfff70000, v4
	ds_bpermute_b32 v10, v26, v25 offset:4
	s_nop 0
	v_addc_co_u32_e32 v7, vcc, -1, v5, vcc
	v_add_co_u32_e32 v30, vcc, 0xfff76000, v4
	global_load_dword v48, v[34:35], off nt
	global_load_dword v50, v[6:7], off nt
	v_addc_co_u32_e32 v31, vcc, -1, v5, vcc
	v_add_co_u32_e32 v6, vcc, 0xfff7c000, v4
	ds_bpermute_b32 v13, v26, v24 offset:8
	s_nop 0
	v_addc_co_u32_e32 v7, vcc, -1, v5, vcc
	v_add_co_u32_e32 v34, vcc, 0xfff82000, v4
	global_load_dword v52, v[30:31], off nt
	global_load_dword v54, v[6:7], off nt
	v_addc_co_u32_e32 v35, vcc, -1, v5, vcc
	v_add_co_u32_e32 v6, vcc, 0xfff88000, v4
	ds_bpermute_b32 v12, v26, v25 offset:8
	s_nop 0
	v_addc_co_u32_e32 v7, vcc, -1, v5, vcc
	v_add_co_u32_e32 v30, vcc, 0xfff8e000, v4
	global_load_dword v56, v[34:35], off nt
	global_load_dword v58, v[6:7], off nt
	v_addc_co_u32_e32 v31, vcc, -1, v5, vcc
	v_add_co_u32_e32 v6, vcc, 0xfff94000, v4
	ds_bpermute_b32 v15, v26, v24 offset:12
	s_nop 0
	v_addc_co_u32_e32 v7, vcc, -1, v5, vcc
	v_add_co_u32_e32 v34, vcc, 0xfff9a000, v4
	global_load_dword v60, v[30:31], off nt
	global_load_dword v62, v[6:7], off nt
	v_addc_co_u32_e32 v35, vcc, -1, v5, vcc
	v_add_co_u32_e32 v6, vcc, 0xfffa0000, v4
	ds_bpermute_b32 v14, v26, v25 offset:12
	s_nop 0
	v_addc_co_u32_e32 v7, vcc, -1, v5, vcc
	v_add_co_u32_e32 v30, vcc, 0xfffa6000, v4
	global_load_dword v64, v[34:35], off nt
	global_load_dword v66, v[6:7], off nt
	v_addc_co_u32_e32 v31, vcc, -1, v5, vcc
	v_add_co_u32_e32 v6, vcc, 0xfffac000, v4
	ds_bpermute_b32 v17, v26, v24 offset:16
	s_nop 0
	v_addc_co_u32_e32 v7, vcc, -1, v5, vcc
	v_add_co_u32_e32 v34, vcc, 0xfffb2000, v4
	global_load_dword v68, v[30:31], off nt
	global_load_dword v70, v[6:7], off nt
	v_addc_co_u32_e32 v35, vcc, -1, v5, vcc
	v_add_co_u32_e32 v6, vcc, 0xfffb8000, v4
	ds_bpermute_b32 v16, v26, v25 offset:16
	s_nop 0
	v_addc_co_u32_e32 v7, vcc, -1, v5, vcc
	v_add_co_u32_e32 v30, vcc, 0xfffbe000, v4
	global_load_dword v72, v[34:35], off nt
	global_load_dword v74, v[6:7], off nt
	v_addc_co_u32_e32 v31, vcc, -1, v5, vcc
	v_add_co_u32_e32 v6, vcc, 0xfffc4000, v4
	ds_bpermute_b32 v19, v26, v24 offset:20
	s_nop 0
	v_addc_co_u32_e32 v7, vcc, -1, v5, vcc
	v_add_co_u32_e32 v34, vcc, 0xfffca000, v4
	global_load_dword v76, v[30:31], off nt
	global_load_dword v78, v[6:7], off nt
	v_addc_co_u32_e32 v35, vcc, -1, v5, vcc
	v_add_co_u32_e32 v6, vcc, 0xfffd0000, v4
	ds_bpermute_b32 v18, v26, v25 offset:20
	s_nop 0
	v_addc_co_u32_e32 v7, vcc, -1, v5, vcc
	v_add_co_u32_e32 v30, vcc, 0xfffd6000, v4
	global_load_dword v80, v[34:35], off nt
	global_load_dword v82, v[6:7], off nt
	v_addc_co_u32_e32 v31, vcc, -1, v5, vcc
	v_add_co_u32_e32 v6, vcc, 0xfffdc000, v4
	global_load_dword v30, v[30:31], off nt
	s_nop 0
	v_addc_co_u32_e32 v7, vcc, -1, v5, vcc
	v_add_co_u32_e32 v34, vcc, 0xfffe2000, v4
	s_waitcnt vmcnt(24) lgkmcnt(10)
	v_pk_fma_f32 v[2:3], v[8:9], v[36:37], v[2:3] op_sel_hi:[1,0,1]
	v_addc_co_u32_e32 v35, vcc, -1, v5, vcc
	v_add_co_u32_e32 v84, vcc, 0xfffe8000, v4
	global_load_dword v86, v[6:7], off nt
	global_load_dword v88, v[34:35], off nt
	v_addc_co_u32_e32 v85, vcc, -1, v5, vcc
	v_add_co_u32_e32 v6, vcc, 0xfffee000, v4
	ds_bpermute_b32 v21, v26, v24 offset:24
	s_nop 0
	v_addc_co_u32_e32 v7, vcc, -1, v5, vcc
	v_add_co_u32_e32 v34, vcc, 0xffff4000, v4
	global_load_dword v90, v[84:85], off nt
	global_load_dword v92, v[6:7], off nt
	v_addc_co_u32_e32 v35, vcc, -1, v5, vcc
	v_add_co_u32_e32 v6, vcc, 0xffffa000, v4
	ds_bpermute_b32 v20, v26, v25 offset:24
	s_nop 0
	v_addc_co_u32_e32 v7, vcc, -1, v5, vcc
	global_load_dword v84, v[34:35], off nt
	global_load_dword v94, v[6:7], off nt
	global_load_dword v96, v[4:5], off nt
	s_waitcnt vmcnt(30) lgkmcnt(10)
	v_pk_fma_f32 v[2:3], v[10:11], v[38:39], v[2:3] op_sel_hi:[1,0,1]
	ds_bpermute_b32 v23, v26, v24 offset:28
	ds_bpermute_b32 v22, v26, v25 offset:28
	s_waitcnt vmcnt(29) lgkmcnt(10)
	v_pk_fma_f32 v[2:3], v[12:13], v[40:41], v[2:3] op_sel_hi:[1,0,1]
	ds_bpermute_b32 v33, v26, v24 offset:32
	ds_bpermute_b32 v32, v26, v25 offset:32
	s_waitcnt vmcnt(28) lgkmcnt(10)
	v_pk_fma_f32 v[2:3], v[14:15], v[42:43], v[2:3] op_sel_hi:[1,0,1]
	ds_bpermute_b32 v7, v26, v24 offset:36
	ds_bpermute_b32 v6, v26, v25 offset:36
	s_waitcnt vmcnt(27) lgkmcnt(10)
	v_pk_fma_f32 v[2:3], v[16:17], v[44:45], v[2:3] op_sel_hi:[1,0,1]
	ds_bpermute_b32 v35, v26, v24 offset:40
	ds_bpermute_b32 v34, v26, v25 offset:40
	s_waitcnt vmcnt(26) lgkmcnt(10)
	v_pk_fma_f32 v[2:3], v[18:19], v[46:47], v[2:3] op_sel_hi:[1,0,1]
	ds_bpermute_b32 v99, v26, v24 offset:44
	ds_bpermute_b32 v98, v26, v25 offset:44
	s_waitcnt vmcnt(25) lgkmcnt(10)
	v_pk_fma_f32 v[2:3], v[20:21], v[48:49], v[2:3] op_sel_hi:[1,0,1]
	ds_bpermute_b32 v101, v26, v24 offset:48
	ds_bpermute_b32 v100, v26, v25 offset:48
	s_waitcnt vmcnt(24) lgkmcnt(10)
	v_pk_fma_f32 v[2:3], v[22:23], v[50:51], v[2:3] op_sel_hi:[1,0,1]
	ds_bpermute_b32 v103, v26, v24 offset:52
	ds_bpermute_b32 v102, v26, v25 offset:52
	s_waitcnt vmcnt(23) lgkmcnt(10)
	v_pk_fma_f32 v[2:3], v[32:33], v[52:53], v[2:3] op_sel_hi:[1,0,1]
	ds_bpermute_b32 v105, v26, v24 offset:56
	ds_bpermute_b32 v104, v26, v25 offset:56
	s_waitcnt vmcnt(22) lgkmcnt(10)
	v_pk_fma_f32 v[2:3], v[6:7], v[54:55], v[2:3] op_sel_hi:[1,0,1]
	ds_bpermute_b32 v107, v26, v24 offset:60
	ds_bpermute_b32 v106, v26, v25 offset:60
	s_waitcnt vmcnt(21) lgkmcnt(10)
	v_pk_fma_f32 v[2:3], v[34:35], v[56:57], v[2:3] op_sel_hi:[1,0,1]
	ds_bpermute_b32 v109, v26, v24 offset:64
	ds_bpermute_b32 v108, v26, v25 offset:64
	s_waitcnt vmcnt(20) lgkmcnt(10)
	v_pk_fma_f32 v[2:3], v[98:99], v[58:59], v[2:3] op_sel_hi:[1,0,1]
	ds_bpermute_b32 v111, v26, v24 offset:68
	ds_bpermute_b32 v110, v26, v25 offset:68
	s_waitcnt vmcnt(19) lgkmcnt(10)
	v_pk_fma_f32 v[2:3], v[100:101], v[60:61], v[2:3] op_sel_hi:[1,0,1]
	ds_bpermute_b32 v113, v26, v24 offset:72
	ds_bpermute_b32 v112, v26, v25 offset:72
	s_waitcnt vmcnt(18) lgkmcnt(10)
	v_pk_fma_f32 v[2:3], v[102:103], v[62:63], v[2:3] op_sel_hi:[1,0,1]
	ds_bpermute_b32 v115, v26, v24 offset:76
	ds_bpermute_b32 v114, v26, v25 offset:76
	s_waitcnt vmcnt(17) lgkmcnt(10)
	v_pk_fma_f32 v[2:3], v[104:105], v[64:65], v[2:3] op_sel_hi:[1,0,1]
	ds_bpermute_b32 v117, v26, v24 offset:80
	ds_bpermute_b32 v116, v26, v25 offset:80
	s_waitcnt vmcnt(16) lgkmcnt(10)
	v_pk_fma_f32 v[2:3], v[106:107], v[66:67], v[2:3] op_sel_hi:[1,0,1]
	ds_bpermute_b32 v119, v26, v24 offset:84
	ds_bpermute_b32 v118, v26, v25 offset:84
	s_waitcnt vmcnt(15) lgkmcnt(10)
	v_pk_fma_f32 v[2:3], v[108:109], v[68:69], v[2:3] op_sel_hi:[1,0,1]
	ds_bpermute_b32 v121, v26, v24 offset:88
	ds_bpermute_b32 v120, v26, v25 offset:88
	s_waitcnt vmcnt(14) lgkmcnt(10)
	v_pk_fma_f32 v[2:3], v[110:111], v[70:71], v[2:3] op_sel_hi:[1,0,1]
	ds_bpermute_b32 v123, v26, v24 offset:92
	ds_bpermute_b32 v122, v26, v25 offset:92
	s_waitcnt vmcnt(13) lgkmcnt(10)
	v_pk_fma_f32 v[2:3], v[112:113], v[72:73], v[2:3] op_sel_hi:[1,0,1]
	ds_bpermute_b32 v125, v26, v24 offset:96
	ds_bpermute_b32 v124, v26, v25 offset:96
	s_waitcnt vmcnt(12) lgkmcnt(10)
	v_pk_fma_f32 v[2:3], v[114:115], v[74:75], v[2:3] op_sel_hi:[1,0,1]
	ds_bpermute_b32 v127, v26, v24 offset:100
	ds_bpermute_b32 v126, v26, v25 offset:100
	s_waitcnt vmcnt(11) lgkmcnt(10)
	v_pk_fma_f32 v[2:3], v[116:117], v[76:77], v[2:3] op_sel_hi:[1,0,1]
	ds_bpermute_b32 v129, v26, v24 offset:104
	ds_bpermute_b32 v128, v26, v25 offset:104
	s_waitcnt vmcnt(10) lgkmcnt(10)
	v_pk_fma_f32 v[2:3], v[118:119], v[78:79], v[2:3] op_sel_hi:[1,0,1]
	ds_bpermute_b32 v131, v26, v24 offset:108
	ds_bpermute_b32 v130, v26, v25 offset:108
	s_waitcnt vmcnt(9) lgkmcnt(10)
	v_pk_fma_f32 v[2:3], v[120:121], v[80:81], v[2:3] op_sel_hi:[1,0,1]
	ds_bpermute_b32 v133, v26, v24 offset:112
	ds_bpermute_b32 v132, v26, v25 offset:112
	s_waitcnt vmcnt(8) lgkmcnt(10)
	v_pk_fma_f32 v[2:3], v[122:123], v[82:83], v[2:3] op_sel_hi:[1,0,1]
	ds_bpermute_b32 v135, v26, v24 offset:116
	ds_bpermute_b32 v134, v26, v25 offset:116
	s_waitcnt vmcnt(7) lgkmcnt(10)
	v_pk_fma_f32 v[2:3], v[124:125], v[30:31], v[2:3] op_sel_hi:[1,0,1]
	ds_bpermute_b32 v137, v26, v24 offset:120
	ds_bpermute_b32 v136, v26, v25 offset:120
	s_waitcnt vmcnt(6) lgkmcnt(10)
	v_pk_fma_f32 v[2:3], v[126:127], v[86:87], v[2:3] op_sel_hi:[1,0,1]
	ds_bpermute_b32 v27, v26, v24 offset:124
	ds_bpermute_b32 v26, v26, v25 offset:124
	s_waitcnt vmcnt(5) lgkmcnt(10)
	v_pk_fma_f32 v[2:3], v[128:129], v[88:89], v[2:3] op_sel_hi:[1,0,1]
	s_addk_i32 s8, 0x80
	s_waitcnt vmcnt(4) lgkmcnt(8)
	v_pk_fma_f32 v[2:3], v[130:131], v[90:91], v[2:3] op_sel_hi:[1,0,1]
	s_cmpk_eq_i32 s8, 0x100
	s_waitcnt vmcnt(3) lgkmcnt(6)
	v_pk_fma_f32 v[2:3], v[132:133], v[92:93], v[2:3] op_sel_hi:[1,0,1]
	v_lshl_add_u64 v[4:5], v[4:5], 0, s[4:5]
	s_waitcnt vmcnt(2) lgkmcnt(4)
	v_pk_fma_f32 v[2:3], v[134:135], v[84:85], v[2:3] op_sel_hi:[1,0,1]
	s_waitcnt vmcnt(1) lgkmcnt(2)
	v_pk_fma_f32 v[2:3], v[136:137], v[94:95], v[2:3] op_sel_hi:[1,0,1]
	s_waitcnt vmcnt(0) lgkmcnt(0)
	v_pk_fma_f32 v[2:3], v[26:27], v[96:97], v[2:3] op_sel_hi:[1,0,1]
	s_cbranch_scc0 .LBB0_14
	s_lshl_b32 s4, s89, 9
	s_add_i32 s4, s4, 0
	v_lshl_add_u32 v4, v202, 2, s4
	ds_write2st64_b32 v4, v3, v2 offset1:1

.LBB0_26:
	v_lshlrev_b32_e32 v2, 3, v0
	s_abs_i32 s1, s3
	v_and_b32_e32 v18, 56, v2
	v_cvt_f32_u32_e32 v2, s1
	v_readlane_b32 s8, v251, 6
	v_lshlrev_b32_e32 v66, 1, v18
	v_mov_b32_e32 v67, 0
	v_rcp_iflag_f32_e32 v2, v2
	v_readlane_b32 s9, v251, 7
	s_xor_b32 s7, s6, s3
	s_ashr_i32 s7, s7, 31
	v_mul_f32_e32 v2, 0x4f7ffffe, v2
	v_lshl_add_u64 v[68:69], s[8:9], 0, v[66:67]
	v_readlane_b32 s8, v251, 4
	v_cvt_u32_f32_e32 v2, v2
	v_readlane_b32 s9, v251, 5
	v_lshl_add_u64 v[74:75], s[92:93], 0, v[66:67]
	v_mul_u32_u24_e32 v18, 0x84, v18
	v_lshl_add_u64 v[70:71], s[8:9], 0, v[66:67]
	v_readlane_b32 s8, v251, 2
	v_readlane_b32 s9, v251, 3
	v_readfirstlane_b32 s10, v2
	v_lshlrev_b32_e32 v19, 2, v199
	v_lshl_add_u64 v[72:73], s[8:9], 0, v[66:67]
	s_sub_i32 s9, 0, s1
	s_mul_i32 s9, s9, s10
	s_mul_hi_u32 s9, s10, s9
	s_abs_i32 s8, s6
	s_add_i32 s10, s10, s9
	s_mul_hi_u32 s9, s8, s10
	s_mul_i32 s10, s9, s1
	s_sub_i32 s8, s8, s10
	s_add_i32 s10, s9, 1
	s_sub_i32 s11, s8, s1
	s_cmp_ge_u32 s8, s1
	s_cselect_b32 s9, s10, s9
	s_cselect_b32 s8, s11, s8
	s_add_i32 s10, s9, 1
	s_cmp_ge_u32 s8, s1
	s_cselect_b32 s1, s10, s9
	s_xor_b32 s1, s1, s7
	s_sub_i32 s1, s1, s7
	s_mul_i32 s3, s1, s3
	s_sub_i32 s3, s6, s3
	s_lshl_b32 s6, s3, 5
	s_ashr_i32 s7, s6, 31
	s_lshl_b64 s[6:7], s[6:7], 2
	v_lshl_or_b32 v10, s1, 6, v199
	s_add_u32 s4, s4, s6
	s_addc_u32 s5, s5, s7
	v_lshlrev_b32_e32 v66, 2, v230
	v_or_b32_e32 v6, 8, v10
	v_lshl_add_u64 v[2:3], s[4:5], 0, v[66:67]
	v_mad_i64_i32 v[4:5], s[4:5], s0, v10, 0
	v_mad_i64_i32 v[6:7], s[4:5], s0, v6, 0
	v_lshl_add_u64 v[4:5], v[4:5], 2, v[2:3]
	v_lshl_add_u64 v[6:7], v[6:7], 2, v[2:3]
	global_load_dwordx4 v[38:41], v[4:5], off nt
	global_load_dwordx4 v[34:37], v[6:7], off nt
	v_or_b32_e32 v4, 16, v10
	v_or_b32_e32 v6, 24, v10
	v_mad_i64_i32 v[4:5], s[4:5], s0, v4, 0
	v_mad_i64_i32 v[6:7], s[4:5], s0, v6, 0
	v_lshl_add_u64 v[4:5], v[4:5], 2, v[2:3]
	v_lshl_add_u64 v[6:7], v[6:7], 2, v[2:3]
	global_load_dwordx4 v[30:33], v[4:5], off nt
	global_load_dwordx4 v[14:17], v[6:7], off nt
	v_or_b32_e32 v4, 32, v10
	v_or_b32_e32 v6, 40, v10
	v_mad_i64_i32 v[4:5], s[4:5], s0, v4, 0
	v_mad_i64_i32 v[6:7], s[4:5], s0, v6, 0
	v_lshl_add_u64 v[4:5], v[4:5], 2, v[2:3]
	v_lshl_add_u64 v[6:7], v[6:7], 2, v[2:3]
	global_load_dwordx4 v[22:25], v[4:5], off nt
	s_nop 0
	global_load_dwordx4 v[6:9], v[6:7], off nt
	v_or_b32_e32 v4, 48, v10
	v_or_b32_e32 v10, 56, v10
	v_mad_i64_i32 v[4:5], s[4:5], s0, v4, 0
	v_mad_i64_i32 v[10:11], s[0:1], s0, v10, 0
	v_lshl_add_u64 v[4:5], v[4:5], 2, v[2:3]
	v_lshl_add_u64 v[2:3], v[10:11], 2, v[2:3]
	global_load_dwordx4 v[10:13], v[4:5], off nt
	s_nop 0
	global_load_dwordx4 v[2:5], v[2:3], off nt
	v_readlane_b32 s0, v251, 8
	s_mov_b32 s1, 0
	s_movk_i32 s13, 0x7fff
	v_add3_u32 v76, s0, v18, v19
	s_lshl_b32 s0, s94, 5
	s_add_i32 s3, s0, 0xfffda000
	s_lshl_b32 s0, s94, 1
	s_add_i32 s12, s0, 0xffffda00
	s_mov_b32 s16, 0xffff0000
	v_mov_b32_e32 v77, 0x3e38aa3b
	s_mov_b32 s18, s94
	s_branch .LBB0_28

.LBB0_52:
	v_cvt_f32_u32_e32 v18, s19
	s_sub_i32 s20, 0, s19
	s_abs_i32 s11, s0
	s_ashr_i32 s10, s0, 31
	v_rcp_iflag_f32_e32 v18, v18
	s_nop 0
	v_mul_f32_e32 v18, 0x4f7ffffe, v18
	v_cvt_u32_f32_e32 v18, v18
	s_nop 0
	v_readfirstlane_b32 s21, v18
	s_mul_i32 s20, s20, s21
	s_mul_hi_u32 s20, s21, s20
	s_add_i32 s21, s21, s20
	s_mul_hi_u32 s20, s11, s21
	s_mul_i32 s21, s20, s19
	s_sub_i32 s11, s11, s21
	s_add_i32 s22, s20, 1
	s_sub_i32 s21, s11, s19
	s_cmp_ge_u32 s11, s19
	s_cselect_b32 s20, s22, s20
	s_cselect_b32 s11, s21, s11
	s_add_i32 s21, s20, 1
	s_cmp_ge_u32 s11, s19
	s_cselect_b32 s11, s21, s20
	s_xor_b32 s11, s11, s10
	s_sub_i32 s10, s11, s10
	s_mul_i32 s11, s10, s19
	s_sub_i32 s0, s0, s11
	s_lshl_b32 s19, s10, 6
	s_lshl_b32 s10, s0, 5
	s_ashr_i32 s11, s10, 31
	s_lshl_b64 s[10:11], s[10:11], 2
	v_or_b32_e32 v62, s19, v199
	s_add_u32 s8, s8, s10
	s_addc_u32 s9, s9, s11
	s_ashr_i32 s0, s19, 31
	v_or_b32_e32 v42, 16, v62
	v_or_b32_e32 v50, 32, v62
	v_lshl_add_u64 v[58:59], s[8:9], 0, v[66:67]
	s_mul_i32 s0, s6, s0
	v_mul_lo_u32 v20, s7, v62
	v_mad_u64_u32 v[18:19], s[8:9], s6, v62, 0
	v_mul_lo_u32 v44, s7, v42
	v_mad_u64_u32 v[42:43], s[8:9], s6, v42, 0
	v_mul_lo_u32 v52, s7, v50
	v_mad_u64_u32 v[50:51], s[8:9], s6, v50, 0
	v_or_b32_e32 v60, 48, v62
	v_add3_u32 v19, v19, s0, v20
	v_or_b32_e32 v20, 8, v62
	v_add3_u32 v43, v43, s0, v44
	v_or_b32_e32 v44, 24, v62
	v_add3_u32 v51, v51, s0, v52
	v_or_b32_e32 v52, 40, v62
	v_mul_lo_u32 v63, s7, v60
	v_mad_u64_u32 v[60:61], s[8:9], s6, v60, 0
	v_or_b32_e32 v62, 56, v62
	v_mul_lo_u32 v26, s7, v20
	v_mad_u64_u32 v[20:21], s[8:9], s6, v20, 0
	v_mul_lo_u32 v46, s7, v44
	v_mad_u64_u32 v[44:45], s[8:9], s6, v44, 0
	v_mul_lo_u32 v54, s7, v52
	v_mad_u64_u32 v[52:53], s[8:9], s6, v52, 0
	v_add3_u32 v61, v61, s0, v63
	v_mul_lo_u32 v64, s7, v62
	v_mad_u64_u32 v[62:63], s[6:7], s6, v62, 0
	v_add3_u32 v21, v21, s0, v26
	v_add3_u32 v45, v45, s0, v46
	v_add3_u32 v53, v53, s0, v54
	v_add3_u32 v63, v63, s0, v64
	v_lshl_add_u64 v[18:19], v[18:19], 2, v[58:59]
	v_lshl_add_u64 v[26:27], v[20:21], 2, v[58:59]
	v_lshl_add_u64 v[42:43], v[42:43], 2, v[58:59]
	v_lshl_add_u64 v[46:47], v[44:45], 2, v[58:59]
	v_lshl_add_u64 v[50:51], v[50:51], 2, v[58:59]
	v_lshl_add_u64 v[54:55], v[52:53], 2, v[58:59]
	v_lshl_add_u64 v[60:61], v[60:61], 2, v[58:59]
	v_lshl_add_u64 v[62:63], v[62:63], 2, v[58:59]
	global_load_dwordx4 v[18:21], v[18:19], off nt
	s_nop 0
	global_load_dwordx4 v[26:29], v[26:27], off nt
	s_nop 0
	global_load_dwordx4 v[42:45], v[42:43], off nt
	s_nop 0
	global_load_dwordx4 v[46:49], v[46:47], off nt
	s_nop 0
	global_load_dwordx4 v[50:53], v[50:51], off nt
	s_nop 0
	global_load_dwordx4 v[54:57], v[54:55], off nt
	s_nop 0
	global_load_dwordx4 v[58:61], v[60:61], off nt
	s_nop 0
	global_load_dwordx4 v[62:65], v[62:63], off nt
	s_cmpk_gt_i32 s18, 0x5ff
	s_mov_b64 s[6:7], -1
	s_cbranch_scc1 .LBB0_36
